# attention: exps and row-sum adds interleaved in the mask-free softmax (on top of v103)
# speedup vs baseline: 1.0136x; 1.0021x over previous
.Lnd_107:
	s_and_b32 s33, s42, 1
	s_mul_i32 s6, s33, 0x9000
	v_add_u32_e32 v199, s6, v187
	v_add_u32_e32 v198, s6, v188
	s_mov_b64 s[54:55], exec
	v_readfirstlane_b32 s4, v186
	s_bitcmp1_b32 s4, 8
	s_cbranch_scc1 .Lab_B
	ds_read_b128 v[216:219], v199 offset:0
	ds_read_b128 v[232:235], v193 offset:0
	ds_read_b128 v[220:223], v199 offset:32
	ds_read_b128 v[236:239], v193 offset:32
	ds_read_b128 v[224:227], v199 offset:64
	ds_read_b128 v[244:247], v193 offset:64
	ds_read_b128 v[228:231], v199 offset:96
	ds_read_b128 v[248:251], v193 offset:96
	s_waitcnt lgkmcnt(6)
	v_mfma_f32_32x32x16_bf16 v[144:159], v[216:219], v[232:235], v[0:15]
	s_waitcnt lgkmcnt(4)
	v_mfma_f32_32x32x16_bf16 v[144:159], v[220:223], v[236:239], v[144:159]
	s_waitcnt lgkmcnt(2)
	v_mfma_f32_32x32x16_bf16 v[144:159], v[224:227], v[244:247], v[144:159]
	s_waitcnt lgkmcnt(0)
	v_mfma_f32_32x32x16_bf16 v[144:159], v[228:231], v[248:251], v[144:159]
	ds_read_b128 v[216:219], v199 offset:9216
	ds_read_b128 v[232:235], v193 offset:36864
	ds_read_b128 v[220:223], v199 offset:9248
	ds_read_b128 v[236:239], v193 offset:36896
	ds_read_b128 v[224:227], v199 offset:9280
	ds_read_b128 v[244:247], v193 offset:36928
	ds_read_b128 v[228:231], v199 offset:9312
	ds_read_b128 v[248:251], v193 offset:36960
	s_nop 3
	v_exp_f32_e32 v144, v144
	v_exp_f32_e32 v145, v145
	v_exp_f32_e32 v146, v146
	v_add_f32_e32 v243, v144, v145
	v_exp_f32_e32 v147, v147
	v_add_f32_e32 v243, v146, v243
	v_exp_f32_e32 v148, v148
	v_add_f32_e32 v243, v147, v243
	v_exp_f32_e32 v149, v149
	v_add_f32_e32 v243, v148, v243
	v_exp_f32_e32 v150, v150
	v_add_f32_e32 v243, v149, v243
	v_exp_f32_e32 v151, v151
	v_add_f32_e32 v243, v150, v243
	v_exp_f32_e32 v152, v152
	v_add_f32_e32 v243, v151, v243
	v_exp_f32_e32 v153, v153
	v_add_f32_e32 v243, v152, v243
	v_exp_f32_e32 v154, v154
	v_add_f32_e32 v243, v153, v243
	v_exp_f32_e32 v155, v155
	v_add_f32_e32 v243, v154, v243
	v_exp_f32_e32 v156, v156
	v_add_f32_e32 v243, v155, v243
	s_waitcnt lgkmcnt(6)
	v_mfma_f32_32x32x16_bf16 v[200:215], v[216:219], v[232:235], v[0:15]
	v_exp_f32_e32 v157, v157
	v_add_f32_e32 v243, v156, v243
	v_exp_f32_e32 v158, v158
	v_add_f32_e32 v243, v157, v243
	s_waitcnt lgkmcnt(4)
	v_mfma_f32_32x32x16_bf16 v[200:215], v[220:223], v[236:239], v[200:215]
	v_exp_f32_e32 v159, v159
	v_add_f32_e32 v243, v158, v243
	v_add_f32_e32 v243, v159, v243
	v_add_f32_e32 v196, v196, v243
	s_waitcnt lgkmcnt(2)
	v_mfma_f32_32x32x16_bf16 v[200:215], v[224:227], v[244:247], v[200:215]
	v_cvt_pk_bf16_f32 v144, v144, v145
	v_cvt_pk_bf16_f32 v145, v146, v147
	v_cvt_pk_bf16_f32 v146, v148, v149
	v_cvt_pk_bf16_f32 v147, v150, v151
	s_waitcnt lgkmcnt(0)
	v_mfma_f32_32x32x16_bf16 v[200:215], v[228:231], v[248:251], v[200:215]
	ds_read_b128 v[216:219], v198 offset:0
	ds_read_b128 v[224:227], v198 offset:4608
	ds_read_b128 v[232:235], v198 offset:9216
	ds_read_b128 v[244:247], v198 offset:13824
	ds_read_b128 v[220:223], v198 offset:32
	ds_read_b128 v[228:231], v198 offset:4640
	ds_read_b128 v[236:239], v198 offset:9248
	ds_read_b128 v[248:251], v198 offset:13856
	v_cvt_pk_bf16_f32 v148, v152, v153
	v_cvt_pk_bf16_f32 v149, v154, v155
	v_cvt_pk_bf16_f32 v150, v156, v157
	v_cvt_pk_bf16_f32 v151, v158, v159
	s_waitcnt lgkmcnt(7)
	v_mfma_f32_32x32x16_bf16 v[112:127], v[216:219], v[144:147], v[112:127]
	v_exp_f32_e32 v200, v200
	v_exp_f32_e32 v201, v201
	v_exp_f32_e32 v202, v202
	v_add_f32_e32 v243, v200, v201
	v_exp_f32_e32 v203, v203
	s_waitcnt lgkmcnt(6)
	v_mfma_f32_32x32x16_bf16 v[80:95], v[224:227], v[144:147], v[80:95]
	v_add_f32_e32 v243, v202, v243
	v_exp_f32_e32 v204, v204
	v_add_f32_e32 v243, v203, v243
	v_exp_f32_e32 v205, v205
	v_add_f32_e32 v243, v204, v243
	s_waitcnt lgkmcnt(5)
	v_mfma_f32_32x32x16_bf16 v[48:63], v[232:235], v[144:147], v[48:63]
	v_exp_f32_e32 v206, v206
	v_add_f32_e32 v243, v205, v243
	v_exp_f32_e32 v207, v207
	v_add_f32_e32 v243, v206, v243
	v_exp_f32_e32 v208, v208
	s_waitcnt lgkmcnt(4)
	v_mfma_f32_32x32x16_bf16 v[16:31], v[244:247], v[144:147], v[16:31]
	v_add_f32_e32 v243, v207, v243
	v_exp_f32_e32 v209, v209
	v_add_f32_e32 v243, v208, v243
	v_exp_f32_e32 v210, v210
	v_add_f32_e32 v243, v209, v243
	s_waitcnt lgkmcnt(3)
	v_mfma_f32_32x32x16_bf16 v[112:127], v[220:223], v[148:151], v[112:127]
	v_exp_f32_e32 v211, v211
	v_add_f32_e32 v243, v210, v243
	v_exp_f32_e32 v212, v212
	v_add_f32_e32 v243, v211, v243
	v_exp_f32_e32 v213, v213
	s_waitcnt lgkmcnt(2)
	v_mfma_f32_32x32x16_bf16 v[80:95], v[228:231], v[148:151], v[80:95]
	v_add_f32_e32 v243, v212, v243
	v_exp_f32_e32 v214, v214
	v_add_f32_e32 v243, v213, v243
	v_exp_f32_e32 v215, v215
	v_add_f32_e32 v243, v214, v243
	s_waitcnt lgkmcnt(1)
	v_mfma_f32_32x32x16_bf16 v[48:63], v[236:239], v[148:151], v[48:63]
	v_add_f32_e32 v243, v215, v243
	v_add_f32_e32 v197, v197, v243
	v_cvt_pk_bf16_f32 v200, v200, v201
	v_cvt_pk_bf16_f32 v201, v202, v203
	v_cvt_pk_bf16_f32 v202, v204, v205
	s_waitcnt lgkmcnt(0)
	v_mfma_f32_32x32x16_bf16 v[16:31], v[248:251], v[148:151], v[16:31]
	v_cvt_pk_bf16_f32 v203, v206, v207
	v_cvt_pk_bf16_f32 v204, v208, v209
	v_cvt_pk_bf16_f32 v205, v210, v211
	v_cvt_pk_bf16_f32 v206, v212, v213
	v_cvt_pk_bf16_f32 v207, v214, v215
	ds_read_b128 v[252:255], v199 offset:4608
	ds_read_b128 v[208:211], v193
	ds_read_b128 v[212:215], v199 offset:4640
	v_mfma_f32_32x32x16_bf16 v[128:143], v[216:219], v[200:203], v[128:143]
	v_mfma_f32_32x32x16_bf16 v[96:111], v[224:227], v[200:203], v[96:111]
	v_mfma_f32_32x32x16_bf16 v[64:79], v[232:235], v[200:203], v[64:79]
	v_mfma_f32_32x32x16_bf16 v[32:47], v[244:247], v[200:203], v[32:47]
	v_mfma_f32_32x32x16_bf16 v[128:143], v[220:223], v[204:207], v[128:143]
	v_mfma_f32_32x32x16_bf16 v[96:111], v[228:231], v[204:207], v[96:111]
	v_mfma_f32_32x32x16_bf16 v[64:79], v[236:239], v[204:207], v[64:79]
	v_mfma_f32_32x32x16_bf16 v[32:47], v[248:251], v[204:207], v[32:47]
	ds_read_b128 v[236:239], v193 offset:32
	ds_read_b128 v[224:227], v199 offset:4672
	ds_read_b128 v[244:247], v193 offset:64
	ds_read_b128 v[228:231], v199 offset:4704
	ds_read_b128 v[248:251], v193 offset:96
	s_waitcnt lgkmcnt(6)
	v_mfma_f32_32x32x16_bf16 v[144:159], v[252:255], v[208:211], v[0:15]
	s_waitcnt lgkmcnt(4)
	v_mfma_f32_32x32x16_bf16 v[144:159], v[212:215], v[236:239], v[144:159]
	s_waitcnt lgkmcnt(2)
	v_mfma_f32_32x32x16_bf16 v[144:159], v[224:227], v[244:247], v[144:159]
	s_waitcnt lgkmcnt(0)
	v_mfma_f32_32x32x16_bf16 v[144:159], v[228:231], v[248:251], v[144:159]
	ds_read_b128 v[216:219], v199 offset:13824
	ds_read_b128 v[232:235], v193 offset:36864
	ds_read_b128 v[220:223], v199 offset:13856
	ds_read_b128 v[236:239], v193 offset:36896
	ds_read_b128 v[224:227], v199 offset:13888
	ds_read_b128 v[244:247], v193 offset:36928
	ds_read_b128 v[228:231], v199 offset:13920
	ds_read_b128 v[248:251], v193 offset:36960
	s_nop 3
	v_exp_f32_e32 v144, v144
	v_exp_f32_e32 v145, v145
	v_exp_f32_e32 v146, v146
	v_add_f32_e32 v243, v144, v145
	v_exp_f32_e32 v147, v147
	v_add_f32_e32 v243, v146, v243
	v_exp_f32_e32 v148, v148
	v_add_f32_e32 v243, v147, v243
	v_exp_f32_e32 v149, v149
	v_add_f32_e32 v243, v148, v243
	v_exp_f32_e32 v150, v150
	v_add_f32_e32 v243, v149, v243
	v_exp_f32_e32 v151, v151
	v_add_f32_e32 v243, v150, v243
	v_exp_f32_e32 v152, v152
	v_add_f32_e32 v243, v151, v243
	v_exp_f32_e32 v153, v153
	v_add_f32_e32 v243, v152, v243
	v_exp_f32_e32 v154, v154
	v_add_f32_e32 v243, v153, v243
	v_exp_f32_e32 v155, v155
	v_add_f32_e32 v243, v154, v243
	v_exp_f32_e32 v156, v156
	v_add_f32_e32 v243, v155, v243
	s_waitcnt lgkmcnt(6)
	v_mfma_f32_32x32x16_bf16 v[200:215], v[216:219], v[232:235], v[0:15]
	v_exp_f32_e32 v157, v157
	v_add_f32_e32 v243, v156, v243
	v_exp_f32_e32 v158, v158
	v_add_f32_e32 v243, v157, v243
	s_waitcnt lgkmcnt(4)
	v_mfma_f32_32x32x16_bf16 v[200:215], v[220:223], v[236:239], v[200:215]
	v_exp_f32_e32 v159, v159
	v_add_f32_e32 v243, v158, v243
	v_add_f32_e32 v243, v159, v243
	v_add_f32_e32 v196, v196, v243
	s_waitcnt lgkmcnt(2)
	v_mfma_f32_32x32x16_bf16 v[200:215], v[224:227], v[244:247], v[200:215]
	v_cvt_pk_bf16_f32 v144, v144, v145
	v_cvt_pk_bf16_f32 v145, v146, v147
	v_cvt_pk_bf16_f32 v146, v148, v149
	v_cvt_pk_bf16_f32 v147, v150, v151
	s_waitcnt lgkmcnt(0)
	v_mfma_f32_32x32x16_bf16 v[200:215], v[228:231], v[248:251], v[200:215]
	ds_read_b128 v[216:219], v198 offset:64
	ds_read_b128 v[224:227], v198 offset:4672
	ds_read_b128 v[232:235], v198 offset:9280
	ds_read_b128 v[244:247], v198 offset:13888
	ds_read_b128 v[220:223], v198 offset:96
	ds_read_b128 v[228:231], v198 offset:4704
	ds_read_b128 v[236:239], v198 offset:9312
	ds_read_b128 v[248:251], v198 offset:13920
	v_cvt_pk_bf16_f32 v148, v152, v153
	v_cvt_pk_bf16_f32 v149, v154, v155
	v_cvt_pk_bf16_f32 v150, v156, v157
	v_cvt_pk_bf16_f32 v151, v158, v159
	s_waitcnt lgkmcnt(7)
	v_mfma_f32_32x32x16_bf16 v[112:127], v[216:219], v[144:147], v[112:127]
	v_exp_f32_e32 v200, v200
	v_exp_f32_e32 v201, v201
	v_exp_f32_e32 v202, v202
	v_add_f32_e32 v243, v200, v201
	v_exp_f32_e32 v203, v203
	s_waitcnt lgkmcnt(6)
	v_mfma_f32_32x32x16_bf16 v[80:95], v[224:227], v[144:147], v[80:95]
	v_add_f32_e32 v243, v202, v243
	v_exp_f32_e32 v204, v204
	v_add_f32_e32 v243, v203, v243
	v_exp_f32_e32 v205, v205
	v_add_f32_e32 v243, v204, v243
	s_waitcnt lgkmcnt(5)
	v_mfma_f32_32x32x16_bf16 v[48:63], v[232:235], v[144:147], v[48:63]
	v_exp_f32_e32 v206, v206
	v_add_f32_e32 v243, v205, v243
	v_exp_f32_e32 v207, v207
	v_add_f32_e32 v243, v206, v243
	v_exp_f32_e32 v208, v208
	s_waitcnt lgkmcnt(4)
	v_mfma_f32_32x32x16_bf16 v[16:31], v[244:247], v[144:147], v[16:31]
	v_add_f32_e32 v243, v207, v243
	v_exp_f32_e32 v209, v209
	v_add_f32_e32 v243, v208, v243
	v_exp_f32_e32 v210, v210
	v_add_f32_e32 v243, v209, v243
	s_waitcnt lgkmcnt(3)
	v_mfma_f32_32x32x16_bf16 v[112:127], v[220:223], v[148:151], v[112:127]
	v_exp_f32_e32 v211, v211
	v_add_f32_e32 v243, v210, v243
	v_exp_f32_e32 v212, v212
	v_add_f32_e32 v243, v211, v243
	v_exp_f32_e32 v213, v213
	s_waitcnt lgkmcnt(2)
	v_mfma_f32_32x32x16_bf16 v[80:95], v[228:231], v[148:151], v[80:95]
	v_add_f32_e32 v243, v212, v243
	v_exp_f32_e32 v214, v214
	v_add_f32_e32 v243, v213, v243
	v_exp_f32_e32 v215, v215
	v_add_f32_e32 v243, v214, v243
	s_waitcnt lgkmcnt(1)
	v_mfma_f32_32x32x16_bf16 v[48:63], v[236:239], v[148:151], v[48:63]
	v_add_f32_e32 v243, v215, v243
	v_add_f32_e32 v197, v197, v243
	v_cvt_pk_bf16_f32 v200, v200, v201
	v_cvt_pk_bf16_f32 v201, v202, v203
	v_cvt_pk_bf16_f32 v202, v204, v205
	s_waitcnt lgkmcnt(0)
	v_mfma_f32_32x32x16_bf16 v[16:31], v[248:251], v[148:151], v[16:31]
	v_cvt_pk_bf16_f32 v203, v206, v207
	v_cvt_pk_bf16_f32 v204, v208, v209
	v_cvt_pk_bf16_f32 v205, v210, v211
	v_cvt_pk_bf16_f32 v206, v212, v213
	v_cvt_pk_bf16_f32 v207, v214, v215
	s_add_i32 s6, s42, 1
	s_waitcnt vmcnt(0)
	s_cmp_eq_u32 s33, 0
	s_cbranch_scc0 .Lqt_s0_1
	v_add_u32_e32 v252, 0x9000, v190
	ds_write_b128 v189, v[160:163] offset:36864
	ds_write2_b64 v252, v[164:165], v[166:167] offset1:2
	ds_write_b128 v189, v[168:171] offset:46080
	v_add_u32_e32 v252, 0xb000, v190
	ds_write2_b64 v252, v[172:173], v[174:175] offset0:128 offset1:130
	s_branch .Lqt_pf_1

.Lab_B0:
	ds_read_b128 v[216:219], v199 offset:0
	ds_read_b128 v[232:235], v193 offset:0
	ds_read_b128 v[220:223], v199 offset:32
	ds_read_b128 v[236:239], v193 offset:32
	ds_read_b128 v[224:227], v199 offset:64
	ds_read_b128 v[244:247], v193 offset:64
	ds_read_b128 v[228:231], v199 offset:96
	ds_read_b128 v[248:251], v193 offset:96
	s_waitcnt lgkmcnt(6)
	v_mfma_f32_32x32x16_bf16 v[144:159], v[216:219], v[232:235], v[0:15]
	s_waitcnt lgkmcnt(4)
	v_mfma_f32_32x32x16_bf16 v[144:159], v[220:223], v[236:239], v[144:159]
	s_waitcnt lgkmcnt(2)
	v_mfma_f32_32x32x16_bf16 v[144:159], v[224:227], v[244:247], v[144:159]
	s_waitcnt lgkmcnt(0)
	v_mfma_f32_32x32x16_bf16 v[144:159], v[228:231], v[248:251], v[144:159]
	ds_read_b128 v[216:219], v199 offset:9216
	ds_read_b128 v[232:235], v193 offset:36864
	ds_read_b128 v[220:223], v199 offset:9248
	ds_read_b128 v[236:239], v193 offset:36896
	ds_read_b128 v[224:227], v199 offset:9280
	ds_read_b128 v[244:247], v193 offset:36928
	ds_read_b128 v[228:231], v199 offset:9312
	ds_read_b128 v[248:251], v193 offset:36960
	s_nop 3
	v_exp_f32_e32 v144, v144
	v_exp_f32_e32 v145, v145
	v_exp_f32_e32 v146, v146
	v_add_f32_e32 v243, v144, v145
	v_exp_f32_e32 v147, v147
	v_add_f32_e32 v243, v146, v243
	v_exp_f32_e32 v148, v148
	v_add_f32_e32 v243, v147, v243
	v_exp_f32_e32 v149, v149
	v_add_f32_e32 v243, v148, v243
	v_exp_f32_e32 v150, v150
	v_add_f32_e32 v243, v149, v243
	v_exp_f32_e32 v151, v151
	v_add_f32_e32 v243, v150, v243
	v_exp_f32_e32 v152, v152
	v_add_f32_e32 v243, v151, v243
	v_exp_f32_e32 v153, v153
	v_add_f32_e32 v243, v152, v243
	v_exp_f32_e32 v154, v154
	v_add_f32_e32 v243, v153, v243
	v_exp_f32_e32 v155, v155
	v_add_f32_e32 v243, v154, v243
	v_exp_f32_e32 v156, v156
	v_add_f32_e32 v243, v155, v243
	s_waitcnt lgkmcnt(6)
	v_mfma_f32_32x32x16_bf16 v[200:215], v[216:219], v[232:235], v[0:15]
	v_exp_f32_e32 v157, v157
	v_add_f32_e32 v243, v156, v243
	v_exp_f32_e32 v158, v158
	v_add_f32_e32 v243, v157, v243
	s_waitcnt lgkmcnt(4)
	v_mfma_f32_32x32x16_bf16 v[200:215], v[220:223], v[236:239], v[200:215]
	v_exp_f32_e32 v159, v159
	v_add_f32_e32 v243, v158, v243
	v_add_f32_e32 v243, v159, v243
	v_add_f32_e32 v196, v196, v243
	s_waitcnt lgkmcnt(2)
	v_mfma_f32_32x32x16_bf16 v[200:215], v[224:227], v[244:247], v[200:215]
	v_cvt_pk_bf16_f32 v144, v144, v145
	v_cvt_pk_bf16_f32 v145, v146, v147
	v_cvt_pk_bf16_f32 v146, v148, v149
	v_cvt_pk_bf16_f32 v147, v150, v151
	s_waitcnt lgkmcnt(0)
	v_mfma_f32_32x32x16_bf16 v[200:215], v[228:231], v[248:251], v[200:215]
	ds_read_b128 v[216:219], v198 offset:0
	ds_read_b128 v[224:227], v198 offset:4608
	ds_read_b128 v[232:235], v198 offset:9216
	ds_read_b128 v[244:247], v198 offset:13824
	ds_read_b128 v[220:223], v198 offset:32
	ds_read_b128 v[228:231], v198 offset:4640
	ds_read_b128 v[236:239], v198 offset:9248
	ds_read_b128 v[248:251], v198 offset:13856
	v_cvt_pk_bf16_f32 v148, v152, v153
	v_cvt_pk_bf16_f32 v149, v154, v155
	v_cvt_pk_bf16_f32 v150, v156, v157
	v_cvt_pk_bf16_f32 v151, v158, v159
	s_waitcnt lgkmcnt(7)
	v_mfma_f32_32x32x16_bf16 v[112:127], v[216:219], v[144:147], v[112:127]
	v_exp_f32_e32 v200, v200
	v_exp_f32_e32 v201, v201
	v_exp_f32_e32 v202, v202
	v_add_f32_e32 v243, v200, v201
	v_exp_f32_e32 v203, v203
	s_waitcnt lgkmcnt(6)
	v_mfma_f32_32x32x16_bf16 v[80:95], v[224:227], v[144:147], v[80:95]
	v_add_f32_e32 v243, v202, v243
	v_exp_f32_e32 v204, v204
	v_add_f32_e32 v243, v203, v243
	v_exp_f32_e32 v205, v205
	v_add_f32_e32 v243, v204, v243
	s_waitcnt lgkmcnt(5)
	v_mfma_f32_32x32x16_bf16 v[48:63], v[232:235], v[144:147], v[48:63]
	v_exp_f32_e32 v206, v206
	v_add_f32_e32 v243, v205, v243
	v_exp_f32_e32 v207, v207
	v_add_f32_e32 v243, v206, v243
	v_exp_f32_e32 v208, v208
	s_waitcnt lgkmcnt(4)
	v_mfma_f32_32x32x16_bf16 v[16:31], v[244:247], v[144:147], v[16:31]
	v_add_f32_e32 v243, v207, v243
	v_exp_f32_e32 v209, v209
	v_add_f32_e32 v243, v208, v243
	v_exp_f32_e32 v210, v210
	v_add_f32_e32 v243, v209, v243
	s_waitcnt lgkmcnt(3)
	v_mfma_f32_32x32x16_bf16 v[112:127], v[220:223], v[148:151], v[112:127]
	v_exp_f32_e32 v211, v211
	v_add_f32_e32 v243, v210, v243
	v_exp_f32_e32 v212, v212
	v_add_f32_e32 v243, v211, v243
	v_exp_f32_e32 v213, v213
	s_waitcnt lgkmcnt(2)
	v_mfma_f32_32x32x16_bf16 v[80:95], v[228:231], v[148:151], v[80:95]
	v_add_f32_e32 v243, v212, v243
	v_exp_f32_e32 v214, v214
	v_add_f32_e32 v243, v213, v243
	v_exp_f32_e32 v215, v215
	v_add_f32_e32 v243, v214, v243
	s_waitcnt lgkmcnt(1)
	v_mfma_f32_32x32x16_bf16 v[48:63], v[236:239], v[148:151], v[48:63]
	v_add_f32_e32 v243, v215, v243
	v_add_f32_e32 v197, v197, v243
	v_cvt_pk_bf16_f32 v200, v200, v201
	v_cvt_pk_bf16_f32 v201, v202, v203
	v_cvt_pk_bf16_f32 v202, v204, v205
	s_waitcnt lgkmcnt(0)
	v_mfma_f32_32x32x16_bf16 v[16:31], v[248:251], v[148:151], v[16:31]
	v_cvt_pk_bf16_f32 v203, v206, v207
	v_cvt_pk_bf16_f32 v204, v208, v209
	v_cvt_pk_bf16_f32 v205, v210, v211
	v_cvt_pk_bf16_f32 v206, v212, v213
	v_cvt_pk_bf16_f32 v207, v214, v215
	ds_read_b128 v[252:255], v199 offset:4608
	ds_read_b128 v[208:211], v193
	ds_read_b128 v[212:215], v199 offset:4640
	v_mfma_f32_32x32x16_bf16 v[128:143], v[216:219], v[200:203], v[128:143]
	v_mfma_f32_32x32x16_bf16 v[96:111], v[224:227], v[200:203], v[96:111]
	v_mfma_f32_32x32x16_bf16 v[64:79], v[232:235], v[200:203], v[64:79]
	v_mfma_f32_32x32x16_bf16 v[32:47], v[244:247], v[200:203], v[32:47]
	v_mfma_f32_32x32x16_bf16 v[128:143], v[220:223], v[204:207], v[128:143]
	v_mfma_f32_32x32x16_bf16 v[96:111], v[228:231], v[204:207], v[96:111]
	v_mfma_f32_32x32x16_bf16 v[64:79], v[236:239], v[204:207], v[64:79]
	v_mfma_f32_32x32x16_bf16 v[32:47], v[248:251], v[204:207], v[32:47]
	ds_read_b128 v[236:239], v193 offset:32
	ds_read_b128 v[224:227], v199 offset:4672
	ds_read_b128 v[244:247], v193 offset:64
	ds_read_b128 v[228:231], v199 offset:4704
	ds_read_b128 v[248:251], v193 offset:96
	s_waitcnt lgkmcnt(6)
	v_mfma_f32_32x32x16_bf16 v[144:159], v[252:255], v[208:211], v[0:15]
	s_waitcnt lgkmcnt(4)
	v_mfma_f32_32x32x16_bf16 v[144:159], v[212:215], v[236:239], v[144:159]
	s_waitcnt lgkmcnt(2)
	v_mfma_f32_32x32x16_bf16 v[144:159], v[224:227], v[244:247], v[144:159]
	s_waitcnt lgkmcnt(0)
	v_mfma_f32_32x32x16_bf16 v[144:159], v[228:231], v[248:251], v[144:159]
	ds_read_b128 v[216:219], v199 offset:13824
	ds_read_b128 v[232:235], v193 offset:36864
	ds_read_b128 v[220:223], v199 offset:13856
	ds_read_b128 v[236:239], v193 offset:36896
	ds_read_b128 v[224:227], v199 offset:13888
	ds_read_b128 v[244:247], v193 offset:36928
	ds_read_b128 v[228:231], v199 offset:13920
	ds_read_b128 v[248:251], v193 offset:36960
	s_nop 3
	v_exp_f32_e32 v144, v144
	v_exp_f32_e32 v145, v145
	v_exp_f32_e32 v146, v146
	v_add_f32_e32 v243, v144, v145
	v_exp_f32_e32 v147, v147
	v_add_f32_e32 v243, v146, v243
	v_exp_f32_e32 v148, v148
	v_add_f32_e32 v243, v147, v243
	v_exp_f32_e32 v149, v149
	v_add_f32_e32 v243, v148, v243
	v_exp_f32_e32 v150, v150
	v_add_f32_e32 v243, v149, v243
	v_exp_f32_e32 v151, v151
	v_add_f32_e32 v243, v150, v243
	v_exp_f32_e32 v152, v152
	v_add_f32_e32 v243, v151, v243
	v_exp_f32_e32 v153, v153
	v_add_f32_e32 v243, v152, v243
	v_exp_f32_e32 v154, v154
	v_add_f32_e32 v243, v153, v243
	v_exp_f32_e32 v155, v155
	v_add_f32_e32 v243, v154, v243
	v_exp_f32_e32 v156, v156
	v_add_f32_e32 v243, v155, v243
	s_waitcnt lgkmcnt(6)
	v_mfma_f32_32x32x16_bf16 v[200:215], v[216:219], v[232:235], v[0:15]
	v_exp_f32_e32 v157, v157
	v_add_f32_e32 v243, v156, v243
	v_exp_f32_e32 v158, v158
	v_add_f32_e32 v243, v157, v243
	s_waitcnt lgkmcnt(4)
	v_mfma_f32_32x32x16_bf16 v[200:215], v[220:223], v[236:239], v[200:215]
	v_exp_f32_e32 v159, v159
	v_add_f32_e32 v243, v158, v243
	v_add_f32_e32 v243, v159, v243
	v_add_f32_e32 v196, v196, v243
	s_waitcnt lgkmcnt(2)
	v_mfma_f32_32x32x16_bf16 v[200:215], v[224:227], v[244:247], v[200:215]
	v_cvt_pk_bf16_f32 v144, v144, v145
	v_cvt_pk_bf16_f32 v145, v146, v147
	v_cvt_pk_bf16_f32 v146, v148, v149
	v_cvt_pk_bf16_f32 v147, v150, v151
	s_waitcnt lgkmcnt(0)
	v_mfma_f32_32x32x16_bf16 v[200:215], v[228:231], v[248:251], v[200:215]
	ds_read_b128 v[216:219], v198 offset:64
	ds_read_b128 v[224:227], v198 offset:4672
	ds_read_b128 v[232:235], v198 offset:9280
	ds_read_b128 v[244:247], v198 offset:13888
	ds_read_b128 v[220:223], v198 offset:96
	ds_read_b128 v[228:231], v198 offset:4704
	ds_read_b128 v[236:239], v198 offset:9312
	ds_read_b128 v[248:251], v198 offset:13920
	v_cvt_pk_bf16_f32 v148, v152, v153
	v_cvt_pk_bf16_f32 v149, v154, v155
	v_cvt_pk_bf16_f32 v150, v156, v157
	v_cvt_pk_bf16_f32 v151, v158, v159
	s_waitcnt lgkmcnt(7)
	v_mfma_f32_32x32x16_bf16 v[112:127], v[216:219], v[144:147], v[112:127]
	v_exp_f32_e32 v200, v200
	v_exp_f32_e32 v201, v201
	v_exp_f32_e32 v202, v202
	v_add_f32_e32 v243, v200, v201
	v_exp_f32_e32 v203, v203
	s_waitcnt lgkmcnt(6)
	v_mfma_f32_32x32x16_bf16 v[80:95], v[224:227], v[144:147], v[80:95]
	v_add_f32_e32 v243, v202, v243
	v_exp_f32_e32 v204, v204
	v_add_f32_e32 v243, v203, v243
	v_exp_f32_e32 v205, v205
	v_add_f32_e32 v243, v204, v243
	s_waitcnt lgkmcnt(5)
	v_mfma_f32_32x32x16_bf16 v[48:63], v[232:235], v[144:147], v[48:63]
	v_exp_f32_e32 v206, v206
	v_add_f32_e32 v243, v205, v243
	v_exp_f32_e32 v207, v207
	v_add_f32_e32 v243, v206, v243
	v_exp_f32_e32 v208, v208
	s_waitcnt lgkmcnt(4)
	v_mfma_f32_32x32x16_bf16 v[16:31], v[244:247], v[144:147], v[16:31]
	v_add_f32_e32 v243, v207, v243
	v_exp_f32_e32 v209, v209
	v_add_f32_e32 v243, v208, v243
	v_exp_f32_e32 v210, v210
	v_add_f32_e32 v243, v209, v243
	s_waitcnt lgkmcnt(3)
	v_mfma_f32_32x32x16_bf16 v[112:127], v[220:223], v[148:151], v[112:127]
	v_exp_f32_e32 v211, v211
	v_add_f32_e32 v243, v210, v243
	v_exp_f32_e32 v212, v212
	v_add_f32_e32 v243, v211, v243
	v_exp_f32_e32 v213, v213
	s_waitcnt lgkmcnt(2)
	v_mfma_f32_32x32x16_bf16 v[80:95], v[228:231], v[148:151], v[80:95]
	v_add_f32_e32 v243, v212, v243
	v_exp_f32_e32 v214, v214
	v_add_f32_e32 v243, v213, v243
	v_exp_f32_e32 v215, v215
	v_add_f32_e32 v243, v214, v243
	s_waitcnt lgkmcnt(1)
	v_mfma_f32_32x32x16_bf16 v[48:63], v[236:239], v[148:151], v[48:63]
	v_add_f32_e32 v243, v215, v243
	v_add_f32_e32 v197, v197, v243
	v_cvt_pk_bf16_f32 v200, v200, v201
	v_cvt_pk_bf16_f32 v201, v202, v203
	v_cvt_pk_bf16_f32 v202, v204, v205
	s_waitcnt lgkmcnt(0)
	v_mfma_f32_32x32x16_bf16 v[16:31], v[248:251], v[148:151], v[16:31]
	v_cvt_pk_bf16_f32 v203, v206, v207
	v_cvt_pk_bf16_f32 v204, v208, v209
	v_cvt_pk_bf16_f32 v205, v210, v211
	v_cvt_pk_bf16_f32 v206, v212, v213
	v_cvt_pk_bf16_f32 v207, v214, v215
	s_add_i32 s6, s42, 1
	s_waitcnt vmcnt(0)
	s_cmp_eq_u32 s33, 0
	s_cbranch_scc0 .Lqt_s0_2
	v_add_u32_e32 v252, 0x9000, v190
	ds_write_b128 v189, v[160:163] offset:36864
	ds_write2_b64 v252, v[164:165], v[166:167] offset1:2
	ds_write_b128 v189, v[168:171] offset:46080
	v_add_u32_e32 v252, 0xb000, v190
	ds_write2_b64 v252, v[172:173], v[174:175] offset0:128 offset1:130
	s_branch .Lqt_pf_2
